# split variant B: GEMM workgroups convert only ffn_w_up L1 after their tiles (3-4 chunks per wave), converter workgroups 61-62 chunks per wave
# speedup vs baseline: 1.0058x; 1.0058x over previous
; #define TR_JOB_GU(W_, WT_, off_, gain_) { constexpr int nnb_ = DFF / 32, nit_ = (DM / 64) * nnb_; \
;     if (r < nit_) { const int kb_ = r / nnb_, nb_ = r % nnb_, c0_ = 32 * nb_; \
;         return TrDesc{(W_) + (size_t)(64 * kb_) * DFF + c0_, (WT_) + (size_t)(256 * (c0_ / 128) + (c0_ % 128) + (off_)) * DM + 64 * kb_, (gain_) + 64 * kb_, DFF, DM}; } r -= nit_; }
; __device__ __forceinline__ TrDesc p0_item(const Params& p, int it) {
;     unsigned char* ws = p.ws;
;     bf16_t* WAB_IN = (bf16_t*)(ws + WS_WAB_IN); bf16_t* WAB_OUT = (bf16_t*)(ws + WS_WAB_OUT); bf16_t* WGU0 = (bf16_t*)(ws + WS_WGU0); bf16_t* WDN0 = (bf16_t*)(ws + WS_WDN0);
;     bf16_t* WCD_IN = (bf16_t*)(ws + WS_WCD_IN); bf16_t* WGU1 = (bf16_t*)(ws + WS_WGU1);
;     bf16_t* WRG = (bf16_t*)(ws + WS_WRG);
;     int r = it;
;     TR_JOB(p.ab_w_in, AB_IN, DM, 0, 6144, WAB_IN, 0, p.norm_mix)
;     TR_JOB(p.ab_w_in, AB_IN, DM, 6160, 6144, WAB_IN, 6144, p.norm_mix)
;     TR_JOB(p.ab_w_out, DM, DM, 0, DM, WAB_OUT, 0, (const float*)nullptr)
;     TR_JOB_GU(p.ffn_w_gate, WGU0, 0, p.norm_ffn)
;     TR_JOB_GU(p.ffn_w_up, WGU0, 128, p.norm_ffn)
;     TR_JOB(p.ffn_w_down, DM, DFF, 0, DM, WDN0, 0, (const float*)nullptr)
;     TR_JOB(p.cd_w_in, CD_IN, DM, 0, CD_IN, WCD_IN, 0, p.norm_mix + DM)
;     TR_JOB_GU(p.ffn_w_gate + (size_t)DM * DFF, WGU1, 0, p.norm_ffn + DM)
;     TR_JOB_GU(p.ffn_w_up + (size_t)DM * DFF, WGU1, 128, p.norm_ffn + DM)
;     TR_JOB(p.cd_w_out, DM, DM, 0, DM, (bf16_t*)(ws + WS_WCD_OUT), 0, (const float*)nullptr)
;     const int mat = r / 32, rr = r % 32, kb_ = rr / 8, nb_ = rr % 8;
;     const float* W = (mat < 8 ? p.rg_w_x : p.rg_w_a) + (size_t)(mat & 7) * 65536;
;     return TrDesc{W + (size_t)(64 * kb_) * 256 + 32 * nb_, WRG + (size_t)mat * 65536 + (size_t)(32 * nb_) * 256 + 64 * kb_, nullptr, 256, 256};
; }
.Lcv_back_1:
.Lcv_job_u0:
	s_load_dwordx2 s[60:61], s[24:25], 0x20
	s_load_dwordx2 s[62:63], s[24:25], 0xb8
	s_load_dwordx2 s[4:5], s[24:25], 0x10
	s_mov_b32 s6, 0xac00
	s_mov_b32 s7, 0x2000
	s_mov_b32 s75, 2
	s_and_b32 s9, s18, 63
	s_lshr_b32 s10, s18, 6
	s_add_i32 s10, s10, 4
	s_and_b32 s10, s10, 7
	s_sub_i32 s74, 85, s10
	s_lshr_b32 s74, s74, 3
	s_add_i32 s74, s74, 1
	s_lshl_b32 s11, s9, 6
	s_mul_i32 s11, s11, s6
	s_lshl_b32 s21, s10, 9
	s_add_u32 s11, s11, s21
	s_mul_i32 s23, s10, 256
	s_add_i32 s23, s23, 128
	s_mul_i32 s23, s23, s7
	s_lshl_b32 s26, s9, 7
	s_add_u32 s23, s23, s26
	s_mov_b32 s70, 0x1000
	s_mov_b32 s71, 0
	s_mov_b32 s72, 0x1000000
	s_mov_b32 s73, 0
	s_waitcnt lgkmcnt(0)
	s_add_u32 s60, s60, s11
	s_addc_u32 s61, s61, 0
	s_add_u32 s62, s62, 0x8100000
	s_addc_u32 s63, s63, 0
	s_add_u32 s62, s62, s23
	s_addc_u32 s63, s63, 0
	s_lshl_b32 s26, s7, 5
	s_add_u32 s64, s62, s26
	s_addc_u32 s65, s63, 0
	s_add_u32 s66, s64, s26
	s_addc_u32 s67, s65, 0
	s_add_u32 s68, s66, s26
	s_addc_u32 s69, s67, 0
	s_lshl_b32 s26, s9, 8
	s_add_u32 s4, s4, s26
	s_addc_u32 s5, s5, 0
	s_mov_b32 s8, 1
	s_branch .Lcv_run
.Lcv_back_2:
.Lcv_job_dn0:
	s_load_dwordx2 s[60:61], s[24:25], 0x28
	s_load_dwordx2 s[62:63], s[24:25], 0xb8
	s_mov_b32 s6, 0x4000
	s_mov_b32 s7, 0x5600
	s_mov_b32 s75, 3
	s_and_b32 s10, s18, 31
	s_lshr_b32 s9, s18, 5
	s_add_i32 s9, s9, 4
	s_and_b32 s9, s9, 15
	s_sub_i32 s74, 171, s9
	s_lshr_b32 s74, s74, 4
	s_add_i32 s74, s74, 1
	s_lshl_b32 s11, s9, 6
	s_mul_i32 s11, s11, s6
	s_lshl_b32 s21, s10, 9
	s_add_u32 s11, s11, s21
	s_lshl_b32 s23, s10, 7
	s_mul_i32 s23, s23, s7
	s_lshl_b32 s26, s9, 7
	s_add_u32 s23, s23, s26
	s_mov_b32 s70, 0x1000000
	s_mov_b32 s71, 0
	s_mov_b32 s72, 0x800
	s_mov_b32 s73, 0
	s_waitcnt lgkmcnt(0)
	s_add_u32 s60, s60, s11
	s_addc_u32 s61, s61, 0
	s_add_u32 s62, s62, 0x12d00000
	s_addc_u32 s63, s63, 0
	s_add_u32 s62, s62, s23
	s_addc_u32 s63, s63, 0
	s_lshl_b32 s26, s7, 5
	s_add_u32 s64, s62, s26
	s_addc_u32 s65, s63, 0
	s_add_u32 s66, s64, s26
	s_addc_u32 s67, s65, 0
	s_add_u32 s68, s66, s26
	s_addc_u32 s69, s67, 0
	s_mov_b32 s8, 0
	s_branch .Lcv_run

; #define TR_JOB_GU(W_, WT_, off_, gain_) { constexpr int nnb_ = DFF / 32, nit_ = (DM / 64) * nnb_; \
;     if (r < nit_) { const int kb_ = r / nnb_, nb_ = r % nnb_, c0_ = 32 * nb_; \
;         return TrDesc{(W_) + (size_t)(64 * kb_) * DFF + c0_, (WT_) + (size_t)(256 * (c0_ / 128) + (c0_ % 128) + (off_)) * DM + 64 * kb_, (gain_) + 64 * kb_, DFF, DM}; } r -= nit_; }
; __device__ __forceinline__ TrDesc p0_item(const Params& p, int it) {
;     unsigned char* ws = p.ws;
;     bf16_t* WAB_IN = (bf16_t*)(ws + WS_WAB_IN); bf16_t* WAB_OUT = (bf16_t*)(ws + WS_WAB_OUT); bf16_t* WGU0 = (bf16_t*)(ws + WS_WGU0); bf16_t* WDN0 = (bf16_t*)(ws + WS_WDN0);
;     bf16_t* WCD_IN = (bf16_t*)(ws + WS_WCD_IN); bf16_t* WGU1 = (bf16_t*)(ws + WS_WGU1);
;     bf16_t* WRG = (bf16_t*)(ws + WS_WRG);
;     int r = it;
;     TR_JOB(p.ab_w_in, AB_IN, DM, 0, 6144, WAB_IN, 0, p.norm_mix)
;     TR_JOB(p.ab_w_in, AB_IN, DM, 6160, 6144, WAB_IN, 6144, p.norm_mix)
;     TR_JOB(p.ab_w_out, DM, DM, 0, DM, WAB_OUT, 0, (const float*)nullptr)
;     TR_JOB_GU(p.ffn_w_gate, WGU0, 0, p.norm_ffn)
;     TR_JOB_GU(p.ffn_w_up, WGU0, 128, p.norm_ffn)
;     TR_JOB(p.ffn_w_down, DM, DFF, 0, DM, WDN0, 0, (const float*)nullptr)
;     TR_JOB(p.cd_w_in, CD_IN, DM, 0, CD_IN, WCD_IN, 0, p.norm_mix + DM)
;     TR_JOB_GU(p.ffn_w_gate + (size_t)DM * DFF, WGU1, 0, p.norm_ffn + DM)
;     TR_JOB_GU(p.ffn_w_up + (size_t)DM * DFF, WGU1, 128, p.norm_ffn + DM)
;     TR_JOB(p.cd_w_out, DM, DM, 0, DM, (bf16_t*)(ws + WS_WCD_OUT), 0, (const float*)nullptr)
;     const int mat = r / 32, rr = r % 32, kb_ = rr / 8, nb_ = rr % 8;
;     const float* W = (mat < 8 ? p.rg_w_x : p.rg_w_a) + (size_t)(mat & 7) * 65536;
;     return TrDesc{W + (size_t)(64 * kb_) * 256 + 32 * nb_, WRG + (size_t)mat * 65536 + (size_t)(32 * nb_) * 256 + 64 * kb_, nullptr, 256, 256};
; }
.Lcv_back_4:
.Lcv_job_g1:
	s_load_dwordx2 s[60:61], s[24:25], 0x18
	s_load_dwordx2 s[62:63], s[24:25], 0xb8
	s_load_dwordx2 s[4:5], s[24:25], 0x10
	s_mov_b32 s6, 0xac00
	s_mov_b32 s7, 0x2000
	s_mov_b32 s75, 5
	s_and_b32 s9, s18, 63
	s_lshr_b32 s10, s18, 6
	s_add_i32 s10, s10, 0
	s_and_b32 s10, s10, 7
	s_sub_i32 s74, 85, s10
	s_lshr_b32 s74, s74, 3
	s_add_i32 s74, s74, 1
	s_lshl_b32 s11, s9, 6
	s_mul_i32 s11, s11, s6
	s_lshl_b32 s21, s10, 9
	s_add_u32 s11, s11, s21
	s_mul_i32 s23, s10, 256
	s_mul_i32 s23, s23, s7
	s_lshl_b32 s26, s9, 7
	s_add_u32 s23, s23, s26
	s_mov_b32 s70, 0x1000
	s_mov_b32 s71, 0
	s_mov_b32 s72, 0x1000000
	s_mov_b32 s73, 0
	s_waitcnt lgkmcnt(0)
	s_add_u32 s60, s60, 0xac00000
	s_addc_u32 s61, s61, 0
	s_add_u32 s60, s60, s11
	s_addc_u32 s61, s61, 0
	s_add_u32 s62, s62, 0x1f300000
	s_addc_u32 s63, s63, 0
	s_add_u32 s62, s62, s23
	s_addc_u32 s63, s63, 0
	s_lshl_b32 s26, s7, 5
	s_add_u32 s64, s62, s26
	s_addc_u32 s65, s63, 0
	s_add_u32 s66, s64, s26
	s_addc_u32 s67, s65, 0
	s_add_u32 s68, s66, s26
	s_addc_u32 s69, s67, 0
	s_add_u32 s4, s4, 0x4000
	s_addc_u32 s5, s5, 0
	s_lshl_b32 s26, s9, 8
	s_add_u32 s4, s4, s26
	s_addc_u32 s5, s5, 0
	s_mov_b32 s8, 1
	s_branch .Lcv_run
.Lcv_back_5:
.Lcv_job_cdo:
	s_load_dwordx2 s[60:61], s[24:25], 0xa0
	s_load_dwordx2 s[62:63], s[24:25], 0xb8
	s_mov_b32 s6, 0x4000
	s_mov_b32 s7, 0x2000
	s_mov_b32 s75, 6
	s_and_b32 s9, s18, 63
	s_lshr_b32 s10, s18, 6
	s_add_i32 s10, s10, 6
	s_and_b32 s10, s10, 7
	s_sub_i32 s74, 31, s10
	s_lshr_b32 s74, s74, 3
	s_add_i32 s74, s74, 1
	s_lshl_b32 s11, s9, 6
	s_mul_i32 s11, s11, s6
	s_lshl_b32 s21, s10, 9
	s_add_u32 s11, s11, s21
	s_mul_i32 s23, s10, 128
	s_mul_i32 s23, s23, s7
	s_lshl_b32 s26, s9, 7
	s_add_u32 s23, s23, s26
	s_mov_b32 s70, 0x1000
	s_mov_b32 s71, 0
	s_mov_b32 s72, 0x800000
	s_mov_b32 s73, 0
	s_waitcnt lgkmcnt(0)
	s_add_u32 s60, s60, s11
	s_addc_u32 s61, s61, 0
	s_add_u32 s62, s62, 0x1d300000
	s_addc_u32 s63, s63, 0
	s_add_u32 s62, s62, s23
	s_addc_u32 s63, s63, 0
	s_lshl_b32 s26, s7, 5
	s_add_u32 s64, s62, s26
	s_addc_u32 s65, s63, 0
	s_add_u32 s66, s64, s26
	s_addc_u32 s67, s65, 0
	s_add_u32 s68, s66, s26
	s_addc_u32 s69, s67, 0
	s_mov_b32 s8, 0
	s_branch .Lcv_run
.Lcv_back_6:
.Lcv_job_rgx:
	s_load_dwordx2 s[60:61], s[24:25], 0x78
	s_load_dwordx2 s[62:63], s[24:25], 0xb8
	s_mov_b32 s6, 0x400
	s_mov_b32 s7, 0x200
	s_mov_b32 s75, 7
	s_sub_i32 s9, s18, 384
	s_cmp_lt_u32 s9, 64
	s_cselect_b32 s74, 1, 0
	s_and_b32 s9, s9, 63
	s_lshr_b32 s10, s9, 3
	s_bfe_u32 s21, s9, 0x20001
	s_and_b32 s26, s9, 1
	s_lshl_b32 s11, s10, 18
	s_lshl_b32 s27, s21, 16
	s_add_u32 s11, s11, s27
	s_lshl_b32 s27, s26, 9
	s_add_u32 s11, s11, s27
	s_lshl_b32 s23, s10, 17
	s_lshl_b32 s27, s26, 16
	s_add_u32 s23, s23, s27
	s_lshl_b32 s27, s21, 7
	s_add_u32 s23, s23, s27
	s_mov_b32 s70, 0
	s_mov_b32 s71, 0
	s_mov_b32 s72, 0
	s_mov_b32 s73, 0
	s_waitcnt lgkmcnt(0)
	s_add_u32 s60, s60, s11
	s_addc_u32 s61, s61, 0
	s_add_u32 s62, s62, 0x2f600000
	s_addc_u32 s63, s63, 0
	s_add_u32 s62, s62, s23
	s_addc_u32 s63, s63, 0
	s_lshl_b32 s26, s7, 5
	s_add_u32 s64, s62, s26
	s_addc_u32 s65, s63, 0
	s_add_u32 s66, s64, s26
	s_addc_u32 s67, s65, 0
	s_add_u32 s68, s66, s26
	s_addc_u32 s69, s67, 0
	s_mov_b32 s8, 0
	s_branch .Lcv_run
.Lcv_back_7:
.Lcv_job_rga:
	s_load_dwordx2 s[60:61], s[24:25], 0x88
	s_load_dwordx2 s[62:63], s[24:25], 0xb8
	s_mov_b32 s6, 0x400
	s_mov_b32 s7, 0x200
	s_mov_b32 s75, 8
	s_sub_i32 s9, s18, 448
	s_cmp_lt_u32 s9, 64
	s_cselect_b32 s74, 1, 0
	s_and_b32 s9, s9, 63
	s_lshr_b32 s10, s9, 3
	s_bfe_u32 s21, s9, 0x20001
	s_and_b32 s26, s9, 1
	s_lshl_b32 s11, s10, 18
	s_lshl_b32 s27, s21, 16
	s_add_u32 s11, s11, s27
	s_lshl_b32 s27, s26, 9
	s_add_u32 s11, s11, s27
	s_lshl_b32 s23, s10, 17
	s_lshl_b32 s27, s26, 16
	s_add_u32 s23, s23, s27
	s_lshl_b32 s27, s21, 7
	s_add_u32 s23, s23, s27
	s_mov_b32 s70, 0
	s_mov_b32 s71, 0
	s_mov_b32 s72, 0
	s_mov_b32 s73, 0
	s_waitcnt lgkmcnt(0)
	s_add_u32 s60, s60, s11
	s_addc_u32 s61, s61, 0
	s_add_u32 s62, s62, 0x2f700000
	s_addc_u32 s63, s63, 0
	s_add_u32 s62, s62, s23
	s_addc_u32 s63, s63, 0
	s_lshl_b32 s26, s7, 5
	s_add_u32 s64, s62, s26
	s_addc_u32 s65, s63, 0
	s_add_u32 s66, s64, s26
	s_addc_u32 s67, s65, 0
	s_add_u32 s68, s66, s26
	s_addc_u32 s69, s67, 0
	s_mov_b32 s8, 0
	s_branch .Lcv_run

; #define LAS __attribute__((address_space(3)))
; __device__ __forceinline__ void p0b_convert(const Params& p, LAS unsigned char* lds, int tw, int ntw, int wave, int lane) {
;     P0Item pi{&p, P0A_ITEMS}; tr_run(pi, tw, ntw, P0_NITEMS - P0A_ITEMS, (LAS float*)(lds + wave * 8704), lane);
; }
.Lcv_ret:
	s_cmp_eq_u32 s75, 0
	s_cbranch_scc1 .Lcv_back_0
	s_cmp_eq_u32 s75, 1
	s_cbranch_scc1 .Lcv_back_1
	s_cmp_eq_u32 s75, 2
	s_cbranch_scc1 .Lcv_back_2
	s_cmp_eq_u32 s75, 3
	s_cbranch_scc1 .Lcv_back_3
	s_cmp_eq_u32 s75, 4
	s_cbranch_scc1 .Lcv_back_4
	s_cmp_eq_u32 s75, 5
	s_cbranch_scc1 .Lcv_back_5
	s_cmp_eq_u32 s75, 6
	s_cbranch_scc1 .Lcv_back_6
	s_cmp_eq_u32 s75, 7
	s_cbranch_scc1 .Lcv_back_7
	s_cmp_eq_u32 s75, 8
	s_cbranch_scc1 .Lcv_back_8

; template <int layer>
; __device__ __forceinline__ void layer_phases(const Params& p, LAS unsigned char* lds, const XcdBarrier& bar, int lo, int hi, int G, int gw, int ngw, int wave, int lane) {
;     ...
;                 if (G == 256) {
;                     if ((int)blockIdx.x < NG) { pg8::StaticOrder S; S.init(MTOK, AB_MAIN, NG, (int)blockIdx.x); pg8::gemm_phase<pg8::EpiBf16<true>, pg8::StaticOrder, true, true>(lds, g, S, E); }
;                     else p0b_convert(p, lds, ((int)blockIdx.x - NG) * NWAVES + wave, (G - NG) * NWAVES, wave, lane);
.Lgs_job_u1:
	s_load_dwordx2 s[60:61], s[24:25], 0x20
	s_load_dwordx2 s[62:63], s[24:25], 0xb8
	s_load_dwordx2 s[4:5], s[24:25], 0x10
	s_mov_b32 s6, 0xac00
	s_mov_b32 s7, 0x2000
	s_mov_b32 s75, 0
	s_and_b32 s9, s18, 63
	s_lshr_b32 s10, s18, 6
	s_add_i32 s10, s10, 0
	s_cmp_ge_u32 s10, 24
	s_cselect_b32 s74, 24, 0
	s_sub_i32 s10, s10, s74
	s_sub_i32 s74, 85, s10
	s_mul_i32 s74, s74, 2731
	s_lshr_b32 s74, s74, 16
	s_add_i32 s74, s74, 1
	s_lshl_b32 s11, s9, 6
	s_mul_i32 s11, s11, s6
	s_lshl_b32 s21, s10, 9
	s_add_u32 s11, s11, s21
	s_mul_i32 s23, s10, 256
	s_add_i32 s23, s23, 128
	s_mul_i32 s23, s23, s7
	s_lshl_b32 s26, s9, 7
	s_add_u32 s23, s23, s26
	s_mov_b32 s70, 0x3000
	s_mov_b32 s71, 0
	s_mov_b32 s72, 0x3000000
	s_mov_b32 s73, 0
	s_waitcnt lgkmcnt(0)
	s_add_u32 s60, s60, 0xac00000
	s_addc_u32 s61, s61, 0
	s_add_u32 s60, s60, s11
	s_addc_u32 s61, s61, 0
	s_add_u32 s62, s62, 0x1f300000
	s_addc_u32 s63, s63, 0
	s_add_u32 s62, s62, s23
	s_addc_u32 s63, s63, 0
	s_lshl_b32 s26, s7, 5
	s_add_u32 s64, s62, s26
	s_addc_u32 s65, s63, 0
	s_add_u32 s66, s64, s26
	s_addc_u32 s67, s65, 0
	s_add_u32 s68, s66, s26
	s_addc_u32 s69, s67, 0
	s_add_u32 s4, s4, 0x4000
	s_addc_u32 s5, s5, 0
	s_lshl_b32 s26, s9, 8
	s_add_u32 s4, s4, s26
	s_addc_u32 s5, s5, 0
	s_mov_b32 s8, 1
	s_branch .Lgs_run
.Lgs_back_0:
	s_branch .Lgs_done

; __device__ __forceinline__ void xcd_barrier_complete(unsigned* bar, unsigned x, unsigned& nloc, unsigned& nx) {
;     const unsigned G = gridDim.x * gridDim.y * gridDim.z;
;     unsigned sum, cnt, mine, sp = 0u;
;     for (;;) {
;         sum = 0u; cnt = 0u; mine = 0u;
; #pragma unroll
;         for (unsigned j = 0; j < 16; ++j) { const unsigned c = xb_ld(&bar[XB_XCNT(j)]); sum += c; cnt += (c > 0u) ? 1u : 0u; mine = (j == x) ? c : mine; }
;         if (sum == G) break;
;         __builtin_amdgcn_s_sleep(1);
;         if ((++sp & 255u) == 0u) { if (xb_ld(&bar[XB_TMO])) break; if (sp > XB_SPIN_CAP) { atomicAdd(&bar[XB_TMO], 1u); break; } }
;     }
;     nloc = mine > 0u ? mine : 1u; nx = cnt > 0u ? cnt : 1u;
; }
; __device__ __forceinline__ void xcd_barrier(const XcdBarrier& b) {
;     asm volatile("s_waitcnt vmcnt(0)" ::: "memory");
;     __syncthreads();
;     if (threadIdx.x == 0) {
;         unsigned* bar = b.bar;
;         __builtin_amdgcn_s_waitcnt(0);
;         unsigned nloc = b.st[0], nx = b.st[1];
;         if (nloc == 0u) { xcd_barrier_complete(bar, b.x, nloc, nx); b.st[0] = nloc; b.st[1] = nx; }
; template <int layer>
; __device__ __forceinline__ void layer_phases(const Params& p, LAS unsigned char* lds, const XcdBarrier& bar, int lo, int hi, int G, int gw, int ngw, int wave, int lane) {
;     ...
;                 if (G == 256) {
;                     if ((int)blockIdx.x < NG) { pg8::StaticOrder S; S.init(MTOK, AB_MAIN, NG, (int)blockIdx.x); pg8::gemm_phase<pg8::EpiBf16<true>, pg8::StaticOrder, true, true>(lds, g, S, E); }
;                     else p0b_convert(p, lds, ((int)blockIdx.x - NG) * NWAVES + wave, (G - NG) * NWAVES, wave, lane);
;                 } else {
;                     p0b_convert(p, lds, gw, ngw, wave, lane); __syncthreads();
;                     pg8::StaticOrder S; S.init(MTOK, AB_MAIN, G, (int)blockIdx.x); pg8::gemm_phase<pg8::EpiBf16<true>, pg8::StaticOrder, true, true>(lds, g, S, E);
;                 }
;             } else {
;                 pg8::Gemm g{U, (const bf16_t*)(ws + WS_WCD_IN), MTOK, CD_IN, DM}; pg8::StaticOrder S; S.init(MTOK, CD_IN, G, (int)blockIdx.x);
;                 pg8::EpiBf16<true> E{PROJ, CD_IN, SSQ + 1 * MTOK};
;                 for (int rep = 0; rep < REP_GEMM; ++rep) { pg8::gemm_phase<pg8::EpiBf16<true>, pg8::StaticOrder, true, true>(lds, g, S, E); __syncthreads(); }
;             }
.Lgs_ret:
	s_cmp_eq_u32 s75, 0
	s_cbranch_scc1 .Lgs_back_0
.Lgs_done:
	v_readlane_b32 s40, v240, 31
	v_readlane_b32 s41, v240, 32
	s_cmp_lt_i32 s41, 3
	v_readlane_b32 s42, v240, 33
	v_readlane_b32 s43, v240, 34
	s_cbranch_scc1 .LBB0_734
	s_waitcnt vmcnt(0)
	s_barrier
	s_mov_b64 s[0:1], exec
	v_readlane_b32 s2, v240, 23
	v_readlane_b32 s3, v240, 24
	s_and_b64 s[2:3], s[0:1], s[2:3]
	s_mov_b64 exec, s[2:3]
	s_cbranch_execz .LBB0_733
	s_add_i32 s2, 0, 0x20160
	s_waitcnt vmcnt(7)
	v_mov_b32_e32 v2, s2
	s_waitcnt vmcnt(0) expcnt(0) lgkmcnt(0)
	ds_read_b32 v4, v2
	s_add_i32 s2, 0, 0x20164
	v_mov_b32_e32 v2, s2
	ds_read_b32 v2, v2
	s_waitcnt lgkmcnt(1)
	v_cmp_ne_u32_e32 vcc, 0, v4
	s_cbranch_vccnz .LBB0_697
	v_readlane_b32 s2, v240, 2
	v_readlane_b32 s3, v240, 3
	s_load_dwordx2 s[6:7], s[2:3], 0x4
	v_readlane_b32 s8, v240, 20
	v_readlane_b32 s9, v240, 21
	s_add_u32 s2, s8, 0x1000
	s_addc_u32 s3, s9, 0
	s_add_u32 s4, s8, 0x1100
	s_addc_u32 s5, s9, 0
	s_waitcnt lgkmcnt(0)
	s_mul_i32 s16, s6, s92
	s_add_u32 s6, s8, 0x1200
	s_mul_i32 s16, s16, s7
	s_addc_u32 s7, s9, 0
	s_add_u32 s8, s8, 0x1300
	s_addc_u32 s9, s9, 0
	s_mov_b32 s17, 1
	v_mov_b32_e32 v18, 0
	s_branch .LBB0_685
